# XCD grid barrier: the acquire-side buffer_inv sc1 is issued before the spin on the release word (CU quiescent: 1 WG per CU, all other waves parked at s_barrier with vmcnt(0)), so its latency overlaps
# speedup vs baseline: 1.0356x; 1.0073x over previous
.LBB0_211:
	s_or_b64 exec, exec, s[4:5]
	v_cvt_f32_u32_e32 v5, v3
	s_waitcnt vmcnt(0)
	v_readfirstlane_b32 s4, v4
	v_sub_u32_e32 v4, 0, v3
	v_rcp_iflag_f32_e32 v5, v5
	v_add_u32_e32 v6, s4, v2
	v_mul_f32_e32 v5, 0x4f7ffffe, v5
	v_cvt_u32_f32_e32 v5, v5
	v_mul_lo_u32 v2, v4, v5
	v_mul_hi_u32 v2, v5, v2
	v_add_u32_e32 v2, v5, v2
	v_mul_hi_u32 v2, v6, v2
	v_mul_lo_u32 v4, v2, v3
	v_sub_u32_e32 v4, v6, v4
	v_add_u32_e32 v5, 1, v2
	v_cmp_ge_u32_e32 vcc, v4, v3
	s_nop 1
	v_cndmask_b32_e32 v2, v2, v5, vcc
	v_sub_u32_e32 v5, v4, v3
	v_cndmask_b32_e32 v4, v4, v5, vcc
	v_add_u32_e32 v5, 1, v2
	v_cmp_ge_u32_e32 vcc, v4, v3
	v_add_u32_e32 v4, 1, v6
	s_nop 0
	v_cndmask_b32_e32 v2, v2, v5, vcc
	v_mul_lo_u32 v5, v3, v2
	v_add_u32_e32 v3, v5, v3
	v_cmp_ne_u32_e32 vcc, v4, v3
	s_and_saveexec_b64 s[4:5], vcc
	s_xor_b64 s[4:5], exec, s[4:5]
	s_cbranch_execz .LBB0_225
	s_waitcnt lgkmcnt(0)
	v_mov_b32_e32 v1, 0x82000
	buffer_inv sc1
	global_load_dword v1, v1, s[84:85] offset:1024 sc1
	s_add_u32 s10, s84, 0x82400
	s_addc_u32 s11, s85, 0
	s_waitcnt vmcnt(0)
	v_cmp_eq_u32_e32 vcc, v1, v2
	s_and_saveexec_b64 s[6:7], vcc
	s_cbranch_execz .LBB0_224
	s_add_u32 s8, s84, 0x80200
	s_addc_u32 s9, s85, 0
	s_mov_b32 s22, 1
	s_mov_b64 s[12:13], 0
	v_mov_b32_e32 v1, 0
	s_branch .LBB0_215

.LBB0_224:
	s_or_b64 exec, exec, s[6:7]
	s_waitcnt vmcnt(0)
	s_waitcnt vmcnt(0)
.LBB0_225:
	s_andn2_saveexec_b64 s[4:5], s[4:5]
	s_cbranch_execz .LBB0_245
	s_mov_b64 s[4:5], exec
	buffer_wbl2 sc1
	s_waitcnt lgkmcnt(0)
	s_waitcnt vmcnt(0)
	buffer_inv sc1
	v_mbcnt_lo_u32_b32 v2, s4, 0
	v_mbcnt_hi_u32_b32 v2, s5, v2
	v_cmp_eq_u32_e32 vcc, 0, v2
	s_and_saveexec_b64 s[6:7], vcc
	s_cbranch_execz .LBB0_228
	s_bcnt1_i32_b64 s4, s[4:5]
	v_mov_b32_e32 v3, 0x83000
	v_mov_b32_e32 v4, s4
	global_atomic_add v3, v3, v4, s[84:85] offset:1024 sc0

.LBB0_242:
	s_or_b64 exec, exec, s[4:5]
	s_mov_b64 s[4:5], exec
	v_mbcnt_lo_u32_b32 v1, s4, 0
	v_mbcnt_hi_u32_b32 v1, s5, v1
	v_cmp_eq_u32_e32 vcc, 0, v1
	s_waitcnt vmcnt(0)
	s_and_saveexec_b64 s[6:7], vcc
	s_cbranch_execz .LBB0_244
	s_bcnt1_i32_b64 s4, s[4:5]
	v_mov_b32_e32 v1, 0x82000
	v_mov_b32_e32 v2, s4
	global_atomic_add v1, v2, s[84:85] offset:1024

.LBB0_690:
	v_readlane_b32 s4, v253, 56
	s_lshl_b32 s4, s4, 8
	v_readlane_b32 s6, v253, 54
	v_readlane_b32 s7, v253, 55
	s_add_u32 s4, s6, s4
	s_addc_u32 s5, s7, 0
	v_mov_b32_e32 v2, 0x1000
	v_mov_b32_e32 v4, 1
	global_atomic_add v4, v2, v4, s[4:5] offset:1024 sc0
	v_cvt_f32_u32_e32 v2, v3
	v_sub_u32_e32 v5, 0, v3
	v_rcp_iflag_f32_e32 v2, v2
	s_nop 0
	v_mul_f32_e32 v2, 0x4f7ffffe, v2
	v_cvt_u32_f32_e32 v2, v2
	v_mul_lo_u32 v5, v5, v2
	v_mul_hi_u32 v5, v2, v5
	v_add_u32_e32 v2, v2, v5
	s_waitcnt vmcnt(0)
	v_mul_hi_u32 v2, v4, v2
	v_mul_lo_u32 v5, v2, v3
	v_sub_u32_e32 v5, v4, v5
	v_add_u32_e32 v6, 1, v2
	v_cmp_ge_u32_e32 vcc, v5, v3
	v_add_u32_e32 v4, 1, v4
	s_nop 0
	v_cndmask_b32_e32 v2, v2, v6, vcc
	v_sub_u32_e32 v6, v5, v3
	v_cndmask_b32_e32 v5, v5, v6, vcc
	v_add_u32_e32 v6, 1, v2
	v_cmp_ge_u32_e32 vcc, v5, v3
	s_nop 1
	v_cndmask_b32_e32 v2, v2, v6, vcc
	v_mul_lo_u32 v5, v3, v2
	v_add_u32_e32 v3, v5, v3
	v_cmp_ne_u32_e32 vcc, v4, v3
	s_and_saveexec_b64 s[6:7], vcc
	s_xor_b64 s[6:7], exec, s[6:7]
	s_cbranch_execz .LBB0_704
	s_waitcnt lgkmcnt(0)
	v_mov_b32_e32 v1, 0x2000
	buffer_inv sc1
	global_load_dword v1, v1, s[4:5] offset:1024 sc1
	s_add_u32 s12, s4, 0x2400
	s_addc_u32 s13, s5, 0
	s_waitcnt vmcnt(0)
	v_cmp_eq_u32_e32 vcc, v1, v2
	s_and_saveexec_b64 s[8:9], vcc
	s_cbranch_execz .LBB0_703
	s_add_u32 s10, s84, 0x80200
	s_addc_u32 s11, s85, 0
	s_mov_b32 s24, 1
	s_mov_b64 s[14:15], 0
	v_mov_b32_e32 v1, 0
	s_branch .LBB0_694

.LBB0_703:
	s_or_b64 exec, exec, s[8:9]
	s_waitcnt vmcnt(0)
	s_waitcnt vmcnt(0)
.LBB0_704:
	s_andn2_saveexec_b64 s[6:7], s[6:7]
	s_cbranch_execz .LBB0_722
	s_mov_b64 s[6:7], exec
	buffer_wbl2 sc1
	s_waitcnt lgkmcnt(0)
	s_waitcnt vmcnt(0)
	buffer_inv sc1
	v_mbcnt_lo_u32_b32 v2, s6, 0
	v_mbcnt_hi_u32_b32 v2, s7, v2
	v_cmp_eq_u32_e32 vcc, 0, v2
	s_and_saveexec_b64 s[8:9], vcc
	s_cbranch_execz .LBB0_707
	s_bcnt1_i32_b64 s6, s[6:7]
	v_mov_b32_e32 v3, 0x83000
	v_mov_b32_e32 v4, s6
	global_atomic_add v3, v3, v4, s[84:85] offset:1024 sc0

.LBB0_721:
	s_or_b64 exec, exec, s[6:7]
	v_mov_b32_e32 v1, 0x2000
	v_mov_b32_e32 v2, 1
	s_waitcnt vmcnt(0)
	global_atomic_add v1, v2, s[4:5] offset:1024
	s_waitcnt vmcnt(0)

.LBB0_1458:
	v_readlane_b32 s0, v253, 56
	s_lshl_b32 s12, s0, 6
	s_lshl_b64 s[2:3], s[12:13], 2
	v_readlane_b32 s0, v253, 54
	v_readlane_b32 s1, v253, 55
	s_add_u32 s6, s0, s2
	s_addc_u32 s7, s1, s3
	global_atomic_add v3, v174, v175, s[6:7] offset:1024 sc0
	v_cvt_f32_u32_e32 v1, v2
	v_sub_u32_e32 v4, 0, v2
	v_rcp_iflag_f32_e32 v1, v1
	s_nop 0
	v_mul_f32_e32 v1, 0x4f7ffffe, v1
	v_cvt_u32_f32_e32 v1, v1
	v_mul_lo_u32 v4, v4, v1
	v_mul_hi_u32 v4, v1, v4
	v_add_u32_e32 v1, v1, v4
	s_waitcnt vmcnt(0)
	v_mul_hi_u32 v1, v3, v1
	v_mul_lo_u32 v4, v1, v2
	v_sub_u32_e32 v4, v3, v4
	v_add_u32_e32 v5, 1, v1
	v_cmp_ge_u32_e32 vcc, v4, v2
	v_add_u32_e32 v3, 1, v3
	s_nop 0
	v_cndmask_b32_e32 v1, v1, v5, vcc
	v_sub_u32_e32 v5, v4, v2
	v_cndmask_b32_e32 v4, v4, v5, vcc
	v_add_u32_e32 v5, 1, v1
	v_cmp_ge_u32_e32 vcc, v4, v2
	s_nop 1
	v_cndmask_b32_e32 v1, v1, v5, vcc
	v_mul_lo_u32 v4, v2, v1
	v_add_u32_e32 v2, v4, v2
	v_cmp_ne_u32_e32 vcc, v3, v2
	s_and_saveexec_b64 s[2:3], vcc
	s_xor_b64 s[8:9], exec, s[2:3]
	s_cbranch_execz .LBB0_1472
	s_waitcnt lgkmcnt(0)
	buffer_inv sc1
	global_load_dword v0, v176, s[6:7] offset:1024 sc1
	s_add_u32 s42, s6, 0x2400
	s_addc_u32 s43, s7, 0
	s_waitcnt vmcnt(0)
	v_cmp_eq_u32_e32 vcc, v0, v1
	s_and_saveexec_b64 s[10:11], vcc
	s_cbranch_execz .LBB0_1471
	s_mov_b32 s2, 1
	s_mov_b64 s[46:47], 0
	s_branch .LBB0_1462

.LBB0_1471:
	s_or_b64 exec, exec, s[10:11]
	s_waitcnt vmcnt(0)
	s_waitcnt vmcnt(0)
.LBB0_1472:
	s_andn2_saveexec_b64 s[2:3], s[8:9]
	s_cbranch_execz .LBB0_1490
	s_mov_b64 s[8:9], exec
	buffer_wbl2 sc1
	s_waitcnt lgkmcnt(0)
	s_waitcnt vmcnt(0)
	buffer_inv sc1
	v_mbcnt_lo_u32_b32 v1, s8, 0
	v_mbcnt_hi_u32_b32 v1, s9, v1
	v_cmp_eq_u32_e32 vcc, 0, v1
	s_and_saveexec_b64 s[10:11], vcc
	s_cbranch_execz .LBB0_1475
	s_bcnt1_i32_b64 s2, s[8:9]
	v_readlane_b32 s0, v254, 42
	v_mov_b32_e32 v2, s2
	v_readlane_b32 s1, v254, 43
	s_nop 4
	global_atomic_add v2, v137, v2, s[0:1] sc0

.LBB0_1489:
	s_or_b64 exec, exec, s[8:9]
	s_waitcnt vmcnt(0)
	global_atomic_add v176, v175, s[6:7] offset:1024
	s_waitcnt vmcnt(0)
